# G1 epilogue: f32 state-output address math (2 v_mad_u64_u32 + v_lshl_add_u64 + 2 v_mov per group) moved behind the branch that skips the plain and state stores, so gate tiles no longer execute it; on
# baseline (speedup 1.0000x reference)
.LBB0_344:
	v_or_b32_e32 v152, s1, v161
	s_lshl_b32 s1, s6, 8
	v_add_u32_e32 v164, s1, v132
	s_andn2_b64 vcc, exec, s[42:43]
	s_movk_i32 s33, 0x1000
	s_cbranch_vccnz .LBB0_348
	v_mad_u64_u32 v[156:157], s[6:7], s0, v132, 0
	v_mov_b32_e32 v166, v157
	v_mad_u64_u32 v[166:167], s[6:7], s0, v1, v[166:167]
	v_mov_b32_e32 v157, v166
	v_lshl_add_u64 v[156:157], v[156:157], 2, v[154:155]
	s_xor_b64 s[6:7], s[4:5], -1
	s_or_b64 s[14:15], s[22:23], s[40:41]
	s_and_b64 s[14:15], s[14:15], s[6:7]
	s_and_saveexec_b64 s[6:7], s[14:15]
	s_cbranch_execz .LBB0_347
	global_store_dwordx4 v[156:157], v[128:131], off
	global_store_dwordx4 v[156:157], v[124:127], off offset:16

.LBB0_352:
	s_nop 1
	v_add_u32_e32 v118, s1, v136
	s_andn2_b64 vcc, exec, s[2:3]
	s_cbranch_vccnz .LBB0_364
	v_mad_u64_u32 v[116:117], s[14:15], s0, v136, 0
	v_mov_b32_e32 v120, v117
	v_mad_u64_u32 v[120:121], s[14:15], s0, v133, v[120:121]
	v_mov_b32_e32 v117, v120
	v_lshl_add_u64 v[116:117], v[116:117], 2, v[154:155]
	s_xor_b64 s[2:3], s[4:5], -1
	s_or_b64 s[14:15], s[22:23], s[40:41]
	s_and_b64 s[14:15], s[14:15], s[2:3]
	s_and_saveexec_b64 s[2:3], s[14:15]
	s_cbranch_execz .LBB0_355
	global_store_dwordx4 v[116:117], v[112:115], off
	global_store_dwordx4 v[116:117], v[108:111], off offset:16

.LBB0_368:
	s_nop 1
	v_add_u32_e32 v102, s1, v138
	s_andn2_b64 vcc, exec, s[2:3]
	s_cbranch_vccnz .LBB0_376
	v_mad_u64_u32 v[100:101], s[14:15], s0, v138, 0
	v_mov_b32_e32 v104, v101
	v_mad_u64_u32 v[104:105], s[14:15], s0, v137, v[104:105]
	v_mov_b32_e32 v101, v104
	v_lshl_add_u64 v[100:101], v[100:101], 2, v[154:155]
	s_xor_b64 s[2:3], s[4:5], -1
	s_or_b64 s[14:15], s[22:23], s[40:41]
	s_and_b64 s[14:15], s[14:15], s[2:3]
	s_and_saveexec_b64 s[2:3], s[14:15]
	s_cbranch_execz .LBB0_371
	global_store_dwordx4 v[100:101], v[96:99], off
	global_store_dwordx4 v[100:101], v[92:95], off offset:16

.LBB0_380:
	s_nop 1
	v_add_u32_e32 v86, s1, v140
	s_andn2_b64 vcc, exec, s[2:3]
	s_cbranch_vccnz .LBB0_388
	v_mad_u64_u32 v[84:85], s[14:15], s0, v140, 0
	v_mov_b32_e32 v88, v85
	v_mad_u64_u32 v[88:89], s[14:15], s0, v139, v[88:89]
	v_mov_b32_e32 v85, v88
	v_lshl_add_u64 v[84:85], v[84:85], 2, v[154:155]
	s_xor_b64 s[2:3], s[4:5], -1
	s_or_b64 s[14:15], s[22:23], s[40:41]
	s_and_b64 s[14:15], s[14:15], s[2:3]
	s_and_saveexec_b64 s[2:3], s[14:15]
	s_cbranch_execz .LBB0_383
	global_store_dwordx4 v[84:85], v[80:83], off
	global_store_dwordx4 v[84:85], v[76:79], off offset:16

.LBB0_392:
	s_nop 1
	v_add_u32_e32 v70, s1, v142
	s_andn2_b64 vcc, exec, s[2:3]
	s_cbranch_vccnz .LBB0_400
	v_mad_u64_u32 v[68:69], s[14:15], s0, v142, 0
	v_mov_b32_e32 v72, v69
	v_mad_u64_u32 v[72:73], s[14:15], s0, v141, v[72:73]
	v_mov_b32_e32 v69, v72
	v_lshl_add_u64 v[68:69], v[68:69], 2, v[154:155]
	s_xor_b64 s[2:3], s[4:5], -1
	s_or_b64 s[14:15], s[22:23], s[40:41]
	s_and_b64 s[14:15], s[14:15], s[2:3]
	s_and_saveexec_b64 s[2:3], s[14:15]
	s_cbranch_execz .LBB0_395
	global_store_dwordx4 v[68:69], v[64:67], off
	global_store_dwordx4 v[68:69], v[60:63], off offset:16

.LBB0_404:
	s_nop 1
	v_add_u32_e32 v54, s1, v144
	s_andn2_b64 vcc, exec, s[2:3]
	s_cbranch_vccnz .LBB0_412
	v_mad_u64_u32 v[52:53], s[14:15], s0, v144, 0
	v_mov_b32_e32 v56, v53
	v_mad_u64_u32 v[56:57], s[14:15], s0, v143, v[56:57]
	v_mov_b32_e32 v53, v56
	v_lshl_add_u64 v[52:53], v[52:53], 2, v[154:155]
	s_xor_b64 s[2:3], s[4:5], -1
	s_or_b64 s[14:15], s[22:23], s[40:41]
	s_and_b64 s[14:15], s[14:15], s[2:3]
	s_and_saveexec_b64 s[2:3], s[14:15]
	s_cbranch_execz .LBB0_407
	global_store_dwordx4 v[52:53], v[48:51], off
	global_store_dwordx4 v[52:53], v[44:47], off offset:16

.LBB0_416:
	s_nop 1
	v_add_u32_e32 v38, s1, v146
	s_andn2_b64 vcc, exec, s[2:3]
	s_cbranch_vccnz .LBB0_424
	v_mad_u64_u32 v[36:37], s[14:15], s0, v146, 0
	v_mov_b32_e32 v40, v37
	v_mad_u64_u32 v[40:41], s[14:15], s0, v145, v[40:41]
	v_mov_b32_e32 v37, v40
	v_lshl_add_u64 v[36:37], v[36:37], 2, v[154:155]
	s_xor_b64 s[2:3], s[4:5], -1
	s_or_b64 s[14:15], s[22:23], s[40:41]
	s_and_b64 s[14:15], s[14:15], s[2:3]
	s_and_saveexec_b64 s[2:3], s[14:15]
	s_cbranch_execz .LBB0_419
	global_store_dwordx4 v[36:37], v[32:35], off
	global_store_dwordx4 v[36:37], v[28:31], off offset:16

.LBB0_428:
	s_nop 1
	v_add_u32_e32 v22, s1, v148
	s_andn2_b64 vcc, exec, s[2:3]
	s_cbranch_vccnz .LBB0_436
	v_mad_u64_u32 v[20:21], s[14:15], s0, v148, 0
	v_mov_b32_e32 v24, v21
	v_mad_u64_u32 v[24:25], s[0:1], s0, v147, v[24:25]
	v_mov_b32_e32 v21, v24
	v_lshl_add_u64 v[20:21], v[20:21], 2, v[154:155]
	s_xor_b64 s[0:1], s[4:5], -1
	s_or_b64 s[2:3], s[22:23], s[40:41]
	s_and_b64 s[0:1], s[2:3], s[0:1]
	s_and_saveexec_b64 s[2:3], s[0:1]
	s_cbranch_execz .LBB0_431
	global_store_dwordx4 v[20:21], v[16:19], off
	global_store_dwordx4 v[20:21], v[12:15], off offset:16
